# gain-load chain removal also in the late weight conversion (attention-phase start): 16 loads in flight per item there too
# speedup vs baseline: 1.0074x; 1.0053x over previous
.LBB0_1025:
	s_andn2_b64 vcc, exec, s[0:1]
	s_cbranch_vccnz .LBB0_1043
	s_cmpk_gt_u32 s15, 0x2a7f
	s_cselect_b64 s[2:3], -1, 0
	s_and_b64 s[0:1], s[2:3], exec
	s_movk_i32 s1, 0xd580
	s_cselect_b32 s1, s1, 0xffffd5c0
	s_cselect_b32 s0, 64, 0
	s_add_i32 s1, s1, s15
	s_lshl_b32 s5, s1, 5
	s_and_b32 s4, s5, 32
	s_lshl_b32 s6, s1, 6
	s_and_b32 s6, s6, 0x380
	s_or_b32 s0, s4, s0
	s_lshl_b32 s1, s1, 2
	s_or_b32 s0, s0, s6
	s_and_b32 s4, s1, 0x7fffffc0
	v_or_b32_e32 v148, s4, v33
	s_lshl_b32 s48, s0, 2
	v_lshl_add_u64 v[28:29], v[40:41], 0, s[48:49]
	v_lshlrev_b64 v[0:1], 12, v[148:149]
	v_lshl_add_u64 v[0:1], v[28:29], 0, v[0:1]
	global_load_dwordx4 v[0:3], v[0:1], off
	v_readlane_b32 s6, v252, 17
	v_readlane_b32 s7, v252, 18
	v_readlane_b32 s52, v252, 21
	v_readlane_b32 s60, v252, 29
	v_cndmask_b32_e64 v4, 0, 1, s[6:7]
	v_readlane_b32 s61, v252, 30
	v_cmp_ne_u32_e64 s[0:1], 1, v4
	s_andn2_b64 vcc, exec, s[6:7]
	v_lshl_add_u64 v[52:53], v[148:149], 2, s[60:61]
	v_readlane_b32 s53, v252, 22
	v_readlane_b32 s54, v252, 23
	v_readlane_b32 s55, v252, 24
	v_readlane_b32 s56, v252, 25
	v_readlane_b32 s57, v252, 26
	v_readlane_b32 s58, v252, 27
	v_readlane_b32 s59, v252, 28
	v_readlane_b32 s62, v252, 31
	v_readlane_b32 s63, v252, 32
	v_readlane_b32 s64, v252, 33
	v_readlane_b32 s65, v252, 34
	v_readlane_b32 s66, v252, 35
	v_readlane_b32 s67, v252, 36
	s_cbranch_vccnz .LBB0_1028
	global_load_dword v96, v[52:53], off
.LBB0_1028:
	v_or_b32_e32 v4, 8, v148
	v_mov_b32_e32 v5, v149
	v_lshlrev_b64 v[4:5], 12, v[4:5]
	v_lshl_add_u64 v[4:5], v[28:29], 0, v[4:5]
	global_load_dwordx4 v[4:7], v[4:5], off
	s_and_b64 vcc, exec, s[0:1]
	s_cbranch_vccnz .LBB0_1030
	global_load_dword v98, v[52:53], off offset:32
.LBB0_1030:
	v_or_b32_e32 v8, 16, v148
	v_mov_b32_e32 v9, v149
	v_lshlrev_b64 v[8:9], 12, v[8:9]
	v_lshl_add_u64 v[8:9], v[28:29], 0, v[8:9]
	global_load_dwordx4 v[8:11], v[8:9], off
	s_and_b64 vcc, exec, s[0:1]
	s_cbranch_vccnz .LBB0_1032
	global_load_dword v100, v[52:53], off offset:64
.LBB0_1032:
	v_or_b32_e32 v12, 24, v148
	v_mov_b32_e32 v13, v149
	v_lshlrev_b64 v[12:13], 12, v[12:13]
	v_lshl_add_u64 v[12:13], v[28:29], 0, v[12:13]
	global_load_dwordx4 v[12:15], v[12:13], off
	s_and_b64 vcc, exec, s[0:1]
	s_cbranch_vccnz .LBB0_1034
	global_load_dword v102, v[52:53], off offset:96
.LBB0_1034:
	v_or_b32_e32 v16, 32, v148
	v_mov_b32_e32 v17, v149
	v_lshlrev_b64 v[16:17], 12, v[16:17]
	v_lshl_add_u64 v[16:17], v[28:29], 0, v[16:17]
	global_load_dwordx4 v[16:19], v[16:17], off
	s_and_b64 vcc, exec, s[0:1]
	s_cbranch_vccnz .LBB0_1036
	global_load_dword v104, v[52:53], off offset:128
.LBB0_1036:
	v_or_b32_e32 v20, 40, v148
	v_mov_b32_e32 v21, v149
	v_lshlrev_b64 v[20:21], 12, v[20:21]
	v_lshl_add_u64 v[20:21], v[28:29], 0, v[20:21]
	global_load_dwordx4 v[20:23], v[20:21], off
	s_and_b64 vcc, exec, s[0:1]
	s_cbranch_vccnz .LBB0_1038
	global_load_dword v106, v[52:53], off offset:160
.LBB0_1038:
	v_or_b32_e32 v24, 48, v148
	v_mov_b32_e32 v25, v149
	v_lshlrev_b64 v[24:25], 12, v[24:25]
	v_lshl_add_u64 v[24:25], v[28:29], 0, v[24:25]
	global_load_dwordx4 v[24:27], v[24:25], off
	s_and_b64 vcc, exec, s[0:1]
	s_cbranch_vccnz .LBB0_1040
	global_load_dword v108, v[52:53], off offset:192
.LBB0_1040:
	v_or_b32_e32 v148, 56, v148
	v_lshlrev_b64 v[30:31], 12, v[148:149]
	v_lshl_add_u64 v[28:29], v[28:29], 0, v[30:31]
	global_load_dwordx4 v[28:31], v[28:29], off
	s_and_b64 vcc, exec, s[0:1]
	s_cbranch_vccnz .LBB0_1042
	global_load_dword v110, v[52:53], off offset:224
	s_waitcnt vmcnt(0)
	v_pk_mul_f32 v[2:3], v[2:3], v[96:97] op_sel_hi:[1,0]
	v_pk_mul_f32 v[0:1], v[0:1], v[96:97] op_sel_hi:[1,0]
	v_pk_mul_f32 v[6:7], v[6:7], v[98:99] op_sel_hi:[1,0]
	v_pk_mul_f32 v[4:5], v[4:5], v[98:99] op_sel_hi:[1,0]
	v_pk_mul_f32 v[10:11], v[10:11], v[100:101] op_sel_hi:[1,0]
	v_pk_mul_f32 v[8:9], v[8:9], v[100:101] op_sel_hi:[1,0]
	v_pk_mul_f32 v[14:15], v[14:15], v[102:103] op_sel_hi:[1,0]
	v_pk_mul_f32 v[12:13], v[12:13], v[102:103] op_sel_hi:[1,0]
	v_pk_mul_f32 v[18:19], v[18:19], v[104:105] op_sel_hi:[1,0]
	v_pk_mul_f32 v[16:17], v[16:17], v[104:105] op_sel_hi:[1,0]
	v_pk_mul_f32 v[22:23], v[22:23], v[106:107] op_sel_hi:[1,0]
	v_pk_mul_f32 v[20:21], v[20:21], v[106:107] op_sel_hi:[1,0]
	v_pk_mul_f32 v[26:27], v[26:27], v[108:109] op_sel_hi:[1,0]
	v_pk_mul_f32 v[24:25], v[24:25], v[108:109] op_sel_hi:[1,0]
	v_pk_mul_f32 v[30:31], v[30:31], v[110:111] op_sel_hi:[1,0]
	v_pk_mul_f32 v[28:29], v[28:29], v[110:111] op_sel_hi:[1,0]

.LBB0_1071:
	s_andn2_b64 vcc, exec, s[0:1]
	s_cbranch_vccnz .LBB0_1089
	s_and_b32 s2, s12, 0x1e0
	s_and_b32 s0, s14, 0xffc0
	v_readlane_b32 s52, v252, 21
	s_add_i32 s48, s0, 0xffff5e00
	s_lshl_b32 s0, s2, 2
	v_readlane_b32 s54, v252, 23
	v_readlane_b32 s55, v252, 24
	s_add_u32 s0, s54, s0
	s_addc_u32 s1, s55, 0
	v_lshlrev_b32_e32 v148, 2, v32
	v_lshl_add_u64 v[0:1], s[0:1], 0, v[148:149]
	s_mov_b64 s[0:1], 0x1a80
	v_or_b32_e32 v4, s48, v33
	v_lshl_add_u64 v[28:29], v[0:1], 0, s[0:1]
	v_mad_u64_u32 v[0:1], s[0:1], v4, s31, v[28:29]
	global_load_dwordx4 v[0:3], v[0:1], off
	v_readlane_b32 s4, v252, 37
	v_readlane_b32 s5, v252, 38
	v_readlane_b32 s53, v252, 22
	v_mov_b32_e32 v148, v4
	v_cndmask_b32_e64 v4, 0, 1, s[4:5]
	v_cmp_ne_u32_e64 s[0:1], 1, v4
	s_andn2_b64 vcc, exec, s[4:5]
	v_lshl_add_u64 v[52:53], v[148:149], 2, s[52:53]
	v_readlane_b32 s56, v252, 25
	v_readlane_b32 s57, v252, 26
	v_readlane_b32 s58, v252, 27
	v_readlane_b32 s59, v252, 28
	v_readlane_b32 s60, v252, 29
	v_readlane_b32 s61, v252, 30
	v_readlane_b32 s62, v252, 31
	v_readlane_b32 s63, v252, 32
	v_readlane_b32 s64, v252, 33
	v_readlane_b32 s65, v252, 34
	v_readlane_b32 s66, v252, 35
	v_readlane_b32 s67, v252, 36
	s_cbranch_vccnz .LBB0_1074
	global_load_dword v96, v[52:53], off
.LBB0_1074:
	v_or_b32_e32 v4, 8, v148
	v_mad_u64_u32 v[4:5], s[4:5], v4, s31, v[28:29]
	global_load_dwordx4 v[4:7], v[4:5], off
	s_and_b64 vcc, exec, s[0:1]
	s_cbranch_vccnz .LBB0_1076
	global_load_dword v98, v[52:53], off offset:32
.LBB0_1076:
	v_or_b32_e32 v8, 16, v148
	v_mad_u64_u32 v[8:9], s[4:5], v8, s31, v[28:29]
	global_load_dwordx4 v[8:11], v[8:9], off
	s_and_b64 vcc, exec, s[0:1]
	s_cbranch_vccnz .LBB0_1078
	global_load_dword v100, v[52:53], off offset:64
.LBB0_1078:
	v_or_b32_e32 v12, 24, v148
	v_mad_u64_u32 v[12:13], s[4:5], v12, s31, v[28:29]
	global_load_dwordx4 v[12:15], v[12:13], off
	s_and_b64 vcc, exec, s[0:1]
	s_cbranch_vccnz .LBB0_1080
	global_load_dword v102, v[52:53], off offset:96
.LBB0_1080:
	v_or_b32_e32 v16, 32, v148
	v_mad_u64_u32 v[16:17], s[4:5], v16, s31, v[28:29]
	global_load_dwordx4 v[16:19], v[16:17], off
	s_and_b64 vcc, exec, s[0:1]
	s_cbranch_vccnz .LBB0_1082
	global_load_dword v104, v[52:53], off offset:128
.LBB0_1082:
	v_or_b32_e32 v20, 40, v148
	v_mad_u64_u32 v[20:21], s[4:5], v20, s31, v[28:29]
	global_load_dwordx4 v[20:23], v[20:21], off
	s_and_b64 vcc, exec, s[0:1]
	s_cbranch_vccnz .LBB0_1084
	global_load_dword v106, v[52:53], off offset:160
.LBB0_1084:
	v_or_b32_e32 v24, 48, v148
	v_mad_u64_u32 v[24:25], s[4:5], v24, s31, v[28:29]
	global_load_dwordx4 v[24:27], v[24:25], off
	s_and_b64 vcc, exec, s[0:1]
	s_cbranch_vccnz .LBB0_1086
	global_load_dword v108, v[52:53], off offset:192
.LBB0_1086:
	v_or_b32_e32 v30, 56, v148
	v_mad_u64_u32 v[28:29], s[4:5], v30, s31, v[28:29]
	global_load_dwordx4 v[28:31], v[28:29], off
	s_and_b64 vcc, exec, s[0:1]
	s_cbranch_vccnz .LBB0_1088
	global_load_dword v110, v[52:53], off offset:224
	s_waitcnt vmcnt(0)
	v_pk_mul_f32 v[2:3], v[2:3], v[96:97] op_sel_hi:[1,0]
	v_pk_mul_f32 v[0:1], v[0:1], v[96:97] op_sel_hi:[1,0]
	v_pk_mul_f32 v[6:7], v[6:7], v[98:99] op_sel_hi:[1,0]
	v_pk_mul_f32 v[4:5], v[4:5], v[98:99] op_sel_hi:[1,0]
	v_pk_mul_f32 v[10:11], v[10:11], v[100:101] op_sel_hi:[1,0]
	v_pk_mul_f32 v[8:9], v[8:9], v[100:101] op_sel_hi:[1,0]
	v_pk_mul_f32 v[14:15], v[14:15], v[102:103] op_sel_hi:[1,0]
	v_pk_mul_f32 v[12:13], v[12:13], v[102:103] op_sel_hi:[1,0]
	v_pk_mul_f32 v[18:19], v[18:19], v[104:105] op_sel_hi:[1,0]
	v_pk_mul_f32 v[16:17], v[16:17], v[104:105] op_sel_hi:[1,0]
	v_pk_mul_f32 v[22:23], v[22:23], v[106:107] op_sel_hi:[1,0]
	v_pk_mul_f32 v[20:21], v[20:21], v[106:107] op_sel_hi:[1,0]
	v_pk_mul_f32 v[26:27], v[26:27], v[108:109] op_sel_hi:[1,0]
	v_pk_mul_f32 v[24:25], v[24:25], v[108:109] op_sel_hi:[1,0]
	v_pk_mul_f32 v[30:31], v[30:31], v[110:111] op_sel_hi:[1,0]
	v_pk_mul_f32 v[28:29], v[28:29], v[110:111] op_sel_hi:[1,0]

.LBB0_1135:
	s_and_b32 s1, s16, 0xffff
	s_mul_i32 s1, s1, 0xba2f
	s_lshr_b32 s5, s1, 23
	s_mul_i32 s1, s5, 0xb0
	s_sub_i32 s1, s16, s1
	s_and_b32 s6, s1, 0xffff
	s_bfe_u32 s1, s1, 0x10002
	s_add_i32 s1, s1, s4
	s_lshl_b32 s1, s1, 3
	s_lshl_b32 s4, s0, 3
	s_load_dwordx2 s[0:1], s[80:81], s1 offset:0x0
	s_lshl_b32 s3, s6, 5
	s_lshl_b32 s6, s6, 4
	s_and_b32 s7, s3, 0x60
	s_and_b32 s6, s6, 0xf80
	s_or_b32 s6, s6, s7
	s_lshl_b32 s16, s5, 6
	s_lshl_b32 s5, s6, 2
	s_waitcnt lgkmcnt(0)
	s_add_u32 s0, s0, s5
	s_addc_u32 s1, s1, 0
	v_lshlrev_b32_e32 v148, 2, v32
	v_or_b32_e32 v30, s16, v33
	v_lshl_add_u64 v[28:29], s[0:1], 0, v[148:149]
	s_movk_i32 s0, 0x2c00
	v_mad_u64_u32 v[0:1], s[0:1], v30, s0, v[28:29]
	global_load_dwordx4 v[0:3], v[0:1], off
	s_load_dwordx2 s[4:5], s[80:81], s4 offset:0x0
	v_lshlrev_b32_e32 v52, 2, v30
	s_waitcnt lgkmcnt(0)
	s_cmp_lg_u64 s[4:5], 0
	s_cselect_b64 s[6:7], -1, 0
	s_cmp_eq_u64 s[4:5], 0
	s_cbranch_scc1 .LBB0_1137
	global_load_dword v96, v52, s[4:5]
.LBB0_1137:
	v_or_b32_e32 v4, 8, v30
	s_movk_i32 s0, 0x2c00
	v_mad_u64_u32 v[4:5], s[0:1], v4, s0, v[28:29]
	global_load_dwordx4 v[4:7], v[4:5], off
	v_cndmask_b32_e64 v8, 0, 1, s[6:7]
	v_cmp_ne_u32_e64 s[0:1], 1, v8
	s_andn2_b64 vcc, exec, s[6:7]
	s_cbranch_vccnz .LBB0_1139
	global_load_dword v98, v52, s[4:5] offset:32
.LBB0_1139:
	v_or_b32_e32 v8, 16, v30
	s_movk_i32 s6, 0x2c00
	v_mad_u64_u32 v[8:9], s[6:7], v8, s6, v[28:29]
	global_load_dwordx4 v[8:11], v[8:9], off
	s_and_b64 vcc, exec, s[0:1]
	s_cbranch_vccnz .LBB0_1141
	global_load_dword v100, v52, s[4:5] offset:64
.LBB0_1141:
	v_or_b32_e32 v12, 24, v30
	s_movk_i32 s6, 0x2c00
	v_mad_u64_u32 v[12:13], s[6:7], v12, s6, v[28:29]
	global_load_dwordx4 v[12:15], v[12:13], off
	s_and_b64 vcc, exec, s[0:1]
	s_cbranch_vccnz .LBB0_1143
	global_load_dword v102, v52, s[4:5] offset:96
.LBB0_1143:
	v_or_b32_e32 v16, 32, v30
	s_movk_i32 s6, 0x2c00
	v_mad_u64_u32 v[16:17], s[6:7], v16, s6, v[28:29]
	global_load_dwordx4 v[16:19], v[16:17], off
	s_and_b64 vcc, exec, s[0:1]
	s_cbranch_vccnz .LBB0_1145
	global_load_dword v104, v52, s[4:5] offset:128
.LBB0_1145:
	v_or_b32_e32 v20, 40, v30
	s_movk_i32 s6, 0x2c00
	v_mad_u64_u32 v[20:21], s[6:7], v20, s6, v[28:29]
	global_load_dwordx4 v[20:23], v[20:21], off
	s_and_b64 vcc, exec, s[0:1]
	s_cbranch_vccnz .LBB0_1147
	global_load_dword v106, v52, s[4:5] offset:160
.LBB0_1147:
	v_or_b32_e32 v24, 48, v30
	s_movk_i32 s6, 0x2c00
	v_mad_u64_u32 v[24:25], s[6:7], v24, s6, v[28:29]
	global_load_dwordx4 v[24:27], v[24:25], off
	s_and_b64 vcc, exec, s[0:1]
	s_cbranch_vccnz .LBB0_1149
	global_load_dword v108, v52, s[4:5] offset:192
.LBB0_1149:
	v_or_b32_e32 v30, 56, v30
	s_movk_i32 s6, 0x2c00
	v_mad_u64_u32 v[28:29], s[6:7], v30, s6, v[28:29]
	global_load_dwordx4 v[28:31], v[28:29], off
	s_and_b64 vcc, exec, s[0:1]
	s_cbranch_vccnz .LBB0_1011
	global_load_dword v110, v52, s[4:5] offset:224
	s_waitcnt vmcnt(0)
	v_pk_mul_f32 v[2:3], v[2:3], v[96:97] op_sel_hi:[1,0]
	v_pk_mul_f32 v[0:1], v[0:1], v[96:97] op_sel_hi:[1,0]
	v_pk_mul_f32 v[6:7], v[6:7], v[98:99] op_sel_hi:[1,0]
	v_pk_mul_f32 v[4:5], v[4:5], v[98:99] op_sel_hi:[1,0]
	v_pk_mul_f32 v[10:11], v[10:11], v[100:101] op_sel_hi:[1,0]
	v_pk_mul_f32 v[8:9], v[8:9], v[100:101] op_sel_hi:[1,0]
	v_pk_mul_f32 v[14:15], v[14:15], v[102:103] op_sel_hi:[1,0]
	v_pk_mul_f32 v[12:13], v[12:13], v[102:103] op_sel_hi:[1,0]
	v_pk_mul_f32 v[18:19], v[18:19], v[104:105] op_sel_hi:[1,0]
	v_pk_mul_f32 v[16:17], v[16:17], v[104:105] op_sel_hi:[1,0]
	v_pk_mul_f32 v[22:23], v[22:23], v[106:107] op_sel_hi:[1,0]
	v_pk_mul_f32 v[20:21], v[20:21], v[106:107] op_sel_hi:[1,0]
	v_pk_mul_f32 v[26:27], v[26:27], v[108:109] op_sel_hi:[1,0]
	v_pk_mul_f32 v[24:25], v[24:25], v[108:109] op_sel_hi:[1,0]
	v_pk_mul_f32 v[30:31], v[30:31], v[110:111] op_sel_hi:[1,0]
	v_pk_mul_f32 v[28:29], v[28:29], v[110:111] op_sel_hi:[1,0]
	s_branch .LBB0_1011
